# P3: EpiRes epilogue rewritten with 8-step x prefetch + counted vmcnt; half the workgroups run ple GEMM before out-proj GEMM
# speedup vs baseline: 1.0116x; 1.0116x over previous
.LBB0_653:
	s_or_b64 exec, exec, s[4:5]
	v_mov_b32_e32 v8, v225
	s_waitcnt lgkmcnt(0)
	v_cndmask_b32_e64 v0, 0, 1, s[16:17]
	s_barrier
	s_barrier
	s_mov_b32 s99, 0
	v_cmp_ne_u32_e64 s[8:9], 1, v0
	s_andn2_b64 vcc, exec, s[16:17]
	v_readfirstlane_b32 s6, v8
	s_cbranch_vccnz .LBB0_659
.Lp3_S2:
	s_ashr_i32 s3, s2, 31
	s_lshr_b32 s3, s3, 29
	s_add_i32 s3, s2, s3
	s_and_b32 s4, s3, -8
	s_sub_i32 s7, s2, s4
	s_cmp_gt_i32 s7, -1
	s_cbranch_scc0 .LBB0_656
	s_lshl_b32 s14, s7, 6
	s_cbranch_execz .LBB0_657
	s_branch .LBB0_658

.LBB0_659:
	s_and_b64 vcc, exec, s[8:9]
	s_cbranch_vccnz .LBB0_695
	s_cmp_lg_u32 s99, 0
	s_cbranch_scc1 .Lp3_A
	s_bitcmp1_b32 s2, 2
	s_cbranch_scc0 .Lp3_A
	s_mov_b32 s99, 1
	s_mov_b64 s[100:101], s[36:37]
	s_branch .LBB0_695
.Lp3_A:
	v_ashrrev_i32_e32 v1, 31, v8
	v_lshrrev_b32_e32 v1, 26, v1
	v_add_u32_e32 v1, v8, v1
	v_ashrrev_i32_e32 v9, 6, v1
	v_bfe_i32 v1, v8, 27, 1
	v_lshlrev_b32_e32 v0, 4, v8
	v_lshrrev_b32_e32 v1, 22, v1
	v_add_u32_e32 v1, v0, v1
	v_and_b32_e32 v1, 0xfffffc00, v1
	v_sub_u32_e32 v1, v0, v1
	v_lshrrev_b32_e32 v2, 4, v1
	v_bitop3_b32 v2, v2, v1, 32 bitop3:0x6c
	v_ashrrev_i32_e32 v1, 31, v1
	v_lshrrev_b32_e32 v1, 26, v1
	v_add_u32_e32 v1, v2, v1
	v_ashrrev_i32_e32 v10, 6, v1
	v_lshlrev_b32_e32 v3, 3, v9
	v_mul_i32_i24_e32 v4, 64, v10
	v_and_b32_e32 v3, -16, v3
	v_sub_u32_e32 v2, v2, v4
	v_mov_b32_e32 v4, 1
	v_add_u32_e32 v1, v10, v3
	v_lshlrev_b32_e32 v3, 5, v9
	v_ashrrev_i16_sdwa v2, v4, sext(v2) dst_sel:DWORD dst_unused:UNUSED_PAD src0_sel:DWORD src1_sel:BYTE_0
	v_and_b32_e32 v3, 32, v3
	v_bfe_i32 v11, v2, 0, 16
	v_and_b32_e32 v6, 3, v10
	s_mov_b32 s3, 0xfffe0
	v_add_lshl_u32 v3, v3, v11, 1
	v_add_u32_e32 v0, 0x2000, v0
	v_lshlrev_b32_e32 v2, 1, v1
	v_lshrrev_b32_e32 v5, 2, v1
	v_and_or_b32 v6, v1, s3, v6
	v_lshl_add_u32 v128, v1, 12, v3
	v_ashrrev_i32_e32 v1, 31, v0
	v_lshrrev_b32_e32 v1, 22, v1
	v_add_u32_e32 v1, v0, v1
	v_ashrrev_i32_e32 v12, 10, v1
	v_mul_i32_i24_e32 v1, 0x400, v12
	v_sub_u32_e32 v0, v0, v1
	v_and_b32_e32 v2, 24, v2
	v_and_b32_e32 v5, 4, v5
	v_lshrrev_b32_e32 v1, 4, v0
	v_or3_b32 v2, v6, v5, v2
	v_bitop3_b32 v0, v1, v0, 32 bitop3:0x6c
	v_lshl_add_u32 v130, v2, 12, v3
	v_ashrrev_i32_e32 v2, 31, v0
	v_lshrrev_b32_e32 v2, 26, v2
	v_add_u32_e32 v2, v0, v2
	v_lshlrev_b32_e32 v1, 3, v12
	v_ashrrev_i32_e32 v13, 6, v2
	v_and_b32_e32 v2, 0xc0, v2
	v_and_b32_e32 v1, -16, v1
	v_sub_u32_e32 v0, v0, v2
	v_add_u32_e32 v1, v13, v1
	v_ashrrev_i16_sdwa v0, v4, sext(v0) dst_sel:DWORD dst_unused:UNUSED_PAD src0_sel:DWORD src1_sel:BYTE_0
	v_and_b32_e32 v4, 3, v13
	s_ashr_i32 s5, s6, 6
	s_ashr_i32 s57, s56, 31
	s_ashr_i32 s59, s58, 31
	s_ashr_i32 s4, s6, 8
	v_and_or_b32 v4, v1, s3, v4
	s_lshl_b32 s3, s5, 10
	s_lshl_b64 s[14:15], s[56:57], 20
	s_lshl_b64 s[16:17], s[58:59], 20
	s_add_u32 s62, s34, s16
	v_lshlrev_b32_e32 v3, 5, v12
	v_bfe_i32 v14, v0, 0, 16
	v_lshlrev_b32_e32 v0, 1, v1
	v_lshrrev_b32_e32 v2, 2, v1
	s_addc_u32 s63, s35, s17
	s_add_i32 s59, s3, 0
	v_and_b32_e32 v3, 32, v3
	v_and_b32_e32 v0, 24, v0
	v_and_b32_e32 v2, 4, v2
	s_add_i32 m0, s59, 0x10000
	v_or3_b32 v0, v4, v2, v0
	v_add_lshl_u32 v2, v3, v14, 1
	global_load_lds_dwordx4 v130, s[62:63]
	s_add_i32 m0, s59, 0x12000
	v_lshl_add_u32 v134, v0, 12, v2
	s_add_u32 s16, s62, 0x80000
	global_load_lds_dwordx4 v134, s[62:63]
	s_addc_u32 s17, s63, 0
	s_add_i32 m0, s59, 0x14000
	v_lshl_add_u32 v132, v1, 12, v2
	global_load_lds_dwordx4 v130, s[16:17]
	s_add_i32 m0, s59, 0x16000
	s_add_u32 s60, s10, s14
	s_addc_u32 s61, s11, s15
	s_add_i32 s66, s59, 0x2000
	global_load_lds_dwordx4 v134, s[16:17]
	s_mov_b32 m0, s59
	s_add_u32 s14, s60, 0x80000
	global_load_lds_dwordx4 v128, s[60:61]
	s_mov_b32 m0, s66
	s_addc_u32 s15, s61, 0
	s_add_i32 s67, s59, 0x4000
	global_load_lds_dwordx4 v132, s[60:61]
	s_mov_b32 m0, s67
	s_add_i32 s68, s59, 0x6000
	global_load_lds_dwordx4 v128, s[14:15]
	s_mov_b32 m0, s68
	v_mov_b32_e32 v131, 0
	global_load_lds_dwordx4 v132, s[14:15]
	v_mov_b32_e32 v135, v131
	v_mov_b32_e32 v129, v131
	v_mov_b32_e32 v133, v131
	s_cmp_eq_u32 s4, 1
	s_mov_b32 s69, 0
	v_lshl_add_u64 v[6:7], s[62:63], 0, v[130:131]
	v_lshl_add_u64 v[4:5], s[62:63], 0, v[134:135]
	v_lshl_add_u64 v[0:1], s[60:61], 0, v[128:129]
	s_cselect_b64 s[14:15], -1, 0
	s_cmp_lg_u32 s4, 1
	v_lshl_add_u64 v[2:3], s[60:61], 0, v[132:133]
	s_cbranch_scc1 .LBB0_662
	s_barrier

.LBB0_675:
	v_lshl_add_u32 v148, s56, 8, v150
	v_lshl_or_b32 v146, s58, 8, v152
	v_xor_b32_e32 v157, 16, v156
	v_xor_b32_e32 v158, 32, v156
	v_lshl_add_u32 v144, v148, 11, v146
	v_lshlrev_b32_e32 v145, 2, v144
	v_lshlrev_b32_e32 v157, 2, v157
	v_lshlrev_b32_e32 v158, 2, v158
	v_lshlrev_b32_e32 v149, 2, v148
	v_lshlrev_b32_e32 v147, 1, v144
	s_mov_b64 s[60:61], s[36:37]
	global_load_dwordx4 v[176:179], v145, s[60:61] offset:0 nt
	global_load_dwordx4 v[180:183], v145, s[60:61] offset:16 nt
	global_load_dwordx4 v[184:187], v145, s[60:61] offset:512 nt
	global_load_dwordx4 v[188:191], v145, s[60:61] offset:528 nt
	s_add_u32 s60, s36, 0x20000
	s_addc_u32 s61, s37, 0
	global_load_dwordx4 v[192:195], v145, s[60:61] offset:0 nt
	global_load_dwordx4 v[196:199], v145, s[60:61] offset:16 nt
	global_load_dwordx4 v[200:203], v145, s[60:61] offset:512 nt
	global_load_dwordx4 v[204:207], v145, s[60:61] offset:528 nt
	s_add_u32 s60, s36, 0x40000
	s_addc_u32 s61, s37, 0
	global_load_dwordx4 v[208:211], v145, s[60:61] offset:0 nt
	global_load_dwordx4 v[212:215], v145, s[60:61] offset:16 nt
	global_load_dwordx4 v[216:219], v145, s[60:61] offset:512 nt
	global_load_dwordx4 v[220:223], v145, s[60:61] offset:528 nt
	s_add_u32 s60, s36, 0x60000
	s_addc_u32 s61, s37, 0
	global_load_dwordx4 v[228:231], v145, s[60:61] offset:0 nt
	global_load_dwordx4 v[232:235], v145, s[60:61] offset:16 nt
	global_load_dwordx4 v[236:239], v145, s[60:61] offset:512 nt
	global_load_dwordx4 v[240:243], v145, s[60:61] offset:528 nt
	s_waitcnt vmcnt(14)
	v_add_f32_e32 v176, v124, v176
	v_add_f32_e32 v177, v125, v177
	v_add_f32_e32 v178, v126, v178
	v_add_f32_e32 v179, v127, v179
	v_add_f32_e32 v180, v120, v180
	v_add_f32_e32 v181, v121, v181
	v_add_f32_e32 v182, v122, v182
	v_add_f32_e32 v183, v123, v183
	v_cvt_pk_bf16_f32 v244, v176, v177
	v_cvt_pk_bf16_f32 v245, v178, v179
	v_cvt_pk_bf16_f32 v246, v180, v181
	v_cvt_pk_bf16_f32 v247, v182, v183
	s_mov_b64 s[62:63], s[12:13]
	v_mul_f32_e32 v160, v177, v177
	v_mul_f32_e32 v161, v179, v179
	v_mul_f32_e32 v162, v181, v181
	v_mul_f32_e32 v163, v183, v183
	v_fmac_f32_e32 v160, v176, v176
	v_fmac_f32_e32 v161, v178, v178
	v_fmac_f32_e32 v162, v180, v180
	v_fmac_f32_e32 v163, v182, v182
	v_add_f32_e32 v160, v160, v161
	v_add_f32_e32 v162, v162, v163
	v_add_f32_e32 v164, v160, v162
	s_add_u32 s60, s36, 0x100000
	s_addc_u32 s61, s37, 0
	global_load_dwordx4 v[176:179], v145, s[60:61] offset:0 nt
	global_load_dwordx4 v[180:183], v145, s[60:61] offset:16 nt
	global_store_dwordx4 v147, v[244:247], s[62:63] offset:0
	s_waitcnt vmcnt(15)
	v_add_f32_e32 v184, v116, v184
	v_add_f32_e32 v185, v117, v185
	v_add_f32_e32 v186, v118, v186
	v_add_f32_e32 v187, v119, v187
	v_add_f32_e32 v188, v112, v188
	v_add_f32_e32 v189, v113, v189
	v_add_f32_e32 v190, v114, v190
	v_add_f32_e32 v191, v115, v191
	v_cvt_pk_bf16_f32 v248, v184, v185
	v_cvt_pk_bf16_f32 v249, v186, v187
	v_cvt_pk_bf16_f32 v250, v188, v189
	v_cvt_pk_bf16_f32 v251, v190, v191
	v_mul_f32_e32 v160, v185, v185
	v_mul_f32_e32 v161, v187, v187
	v_mul_f32_e32 v162, v189, v189
	v_mul_f32_e32 v163, v191, v191
	v_fmac_f32_e32 v160, v184, v184
	v_fmac_f32_e32 v161, v186, v186
	v_fmac_f32_e32 v162, v188, v188
	v_fmac_f32_e32 v163, v190, v190
	v_add_f32_e32 v160, v160, v161
	v_add_f32_e32 v162, v162, v163
	v_add_f32_e32 v165, v160, v162
	global_load_dwordx4 v[184:187], v145, s[60:61] offset:512 nt
	global_load_dwordx4 v[188:191], v145, s[60:61] offset:528 nt
	global_store_dwordx4 v147, v[248:251], s[62:63] offset:256
	v_add_f32_e32 v166, v164, v165
	ds_bpermute_b32 v167, v157, v166
	s_waitcnt lgkmcnt(0)
	v_add_f32_e32 v166, v166, v167
	ds_bpermute_b32 v167, v158, v166
	s_waitcnt lgkmcnt(0)
	v_add_f32_e32 v168, v166, v167
	s_and_saveexec_b64 s[56:57], s[4:5]
	global_atomic_add_f32 v149, v168, s[22:23] offset:0
	s_or_b64 exec, exec, s[56:57]
	s_waitcnt vmcnt(17)
	v_add_f32_e32 v192, v108, v192
	v_add_f32_e32 v193, v109, v193
	v_add_f32_e32 v194, v110, v194
	v_add_f32_e32 v195, v111, v195
	v_add_f32_e32 v196, v104, v196
	v_add_f32_e32 v197, v105, v197
	v_add_f32_e32 v198, v106, v198
	v_add_f32_e32 v199, v107, v199
	v_cvt_pk_bf16_f32 v244, v192, v193
	v_cvt_pk_bf16_f32 v245, v194, v195
	v_cvt_pk_bf16_f32 v246, v196, v197
	v_cvt_pk_bf16_f32 v247, v198, v199
	s_add_u32 s62, s12, 0x10000
	s_addc_u32 s63, s13, 0
	v_mul_f32_e32 v160, v193, v193
	v_mul_f32_e32 v161, v195, v195
	v_mul_f32_e32 v162, v197, v197
	v_mul_f32_e32 v163, v199, v199
	v_fmac_f32_e32 v160, v192, v192
	v_fmac_f32_e32 v161, v194, v194
	v_fmac_f32_e32 v162, v196, v196
	v_fmac_f32_e32 v163, v198, v198
	v_add_f32_e32 v160, v160, v161
	v_add_f32_e32 v162, v162, v163
	v_add_f32_e32 v164, v160, v162
	s_add_u32 s60, s36, 0x120000
	s_addc_u32 s61, s37, 0
	global_load_dwordx4 v[192:195], v145, s[60:61] offset:0 nt
	global_load_dwordx4 v[196:199], v145, s[60:61] offset:16 nt
	global_store_dwordx4 v147, v[244:247], s[62:63] offset:0
	s_waitcnt vmcnt(18)
	v_add_f32_e32 v200, v100, v200
	v_add_f32_e32 v201, v101, v201
	v_add_f32_e32 v202, v102, v202
	v_add_f32_e32 v203, v103, v203
	v_add_f32_e32 v204, v96, v204
	v_add_f32_e32 v205, v97, v205
	v_add_f32_e32 v206, v98, v206
	v_add_f32_e32 v207, v99, v207
	v_cvt_pk_bf16_f32 v248, v200, v201
	v_cvt_pk_bf16_f32 v249, v202, v203
	v_cvt_pk_bf16_f32 v250, v204, v205
	v_cvt_pk_bf16_f32 v251, v206, v207
	v_mul_f32_e32 v160, v201, v201
	v_mul_f32_e32 v161, v203, v203
	v_mul_f32_e32 v162, v205, v205
	v_mul_f32_e32 v163, v207, v207
	v_fmac_f32_e32 v160, v200, v200
	v_fmac_f32_e32 v161, v202, v202
	v_fmac_f32_e32 v162, v204, v204
	v_fmac_f32_e32 v163, v206, v206
	v_add_f32_e32 v160, v160, v161
	v_add_f32_e32 v162, v162, v163
	v_add_f32_e32 v165, v160, v162
	global_load_dwordx4 v[200:203], v145, s[60:61] offset:512 nt
	global_load_dwordx4 v[204:207], v145, s[60:61] offset:528 nt
	global_store_dwordx4 v147, v[248:251], s[62:63] offset:256
	v_add_f32_e32 v166, v164, v165
	ds_bpermute_b32 v167, v157, v166
	s_waitcnt lgkmcnt(0)
	v_add_f32_e32 v166, v166, v167
	ds_bpermute_b32 v167, v158, v166
	s_waitcnt lgkmcnt(0)
	v_add_f32_e32 v168, v166, v167
	s_and_saveexec_b64 s[56:57], s[4:5]
	global_atomic_add_f32 v149, v168, s[22:23] offset:64
	s_or_b64 exec, exec, s[56:57]
	s_waitcnt vmcnt(20)
	v_add_f32_e32 v208, v92, v208
	v_add_f32_e32 v209, v93, v209
	v_add_f32_e32 v210, v94, v210
	v_add_f32_e32 v211, v95, v211
	v_add_f32_e32 v212, v88, v212
	v_add_f32_e32 v213, v89, v213
	v_add_f32_e32 v214, v90, v214
	v_add_f32_e32 v215, v91, v215
	v_cvt_pk_bf16_f32 v244, v208, v209
	v_cvt_pk_bf16_f32 v245, v210, v211
	v_cvt_pk_bf16_f32 v246, v212, v213
	v_cvt_pk_bf16_f32 v247, v214, v215
	s_add_u32 s62, s12, 0x20000
	s_addc_u32 s63, s13, 0
	v_mul_f32_e32 v160, v209, v209
	v_mul_f32_e32 v161, v211, v211
	v_mul_f32_e32 v162, v213, v213
	v_mul_f32_e32 v163, v215, v215
	v_fmac_f32_e32 v160, v208, v208
	v_fmac_f32_e32 v161, v210, v210
	v_fmac_f32_e32 v162, v212, v212
	v_fmac_f32_e32 v163, v214, v214
	v_add_f32_e32 v160, v160, v161
	v_add_f32_e32 v162, v162, v163
	v_add_f32_e32 v164, v160, v162
	s_add_u32 s60, s36, 0x140000
	s_addc_u32 s61, s37, 0
	global_load_dwordx4 v[208:211], v145, s[60:61] offset:0 nt
	global_load_dwordx4 v[212:215], v145, s[60:61] offset:16 nt
	global_store_dwordx4 v147, v[244:247], s[62:63] offset:0
	s_waitcnt vmcnt(21)
	v_add_f32_e32 v216, v84, v216
	v_add_f32_e32 v217, v85, v217
	v_add_f32_e32 v218, v86, v218
	v_add_f32_e32 v219, v87, v219
	v_add_f32_e32 v220, v80, v220
	v_add_f32_e32 v221, v81, v221
	v_add_f32_e32 v222, v82, v222
	v_add_f32_e32 v223, v83, v223
	v_cvt_pk_bf16_f32 v248, v216, v217
	v_cvt_pk_bf16_f32 v249, v218, v219
	v_cvt_pk_bf16_f32 v250, v220, v221
	v_cvt_pk_bf16_f32 v251, v222, v223
	v_mul_f32_e32 v160, v217, v217
	v_mul_f32_e32 v161, v219, v219
	v_mul_f32_e32 v162, v221, v221
	v_mul_f32_e32 v163, v223, v223
	v_fmac_f32_e32 v160, v216, v216
	v_fmac_f32_e32 v161, v218, v218
	v_fmac_f32_e32 v162, v220, v220
	v_fmac_f32_e32 v163, v222, v222
	v_add_f32_e32 v160, v160, v161
	v_add_f32_e32 v162, v162, v163
	v_add_f32_e32 v165, v160, v162
	global_load_dwordx4 v[216:219], v145, s[60:61] offset:512 nt
	global_load_dwordx4 v[220:223], v145, s[60:61] offset:528 nt
	global_store_dwordx4 v147, v[248:251], s[62:63] offset:256
	v_add_f32_e32 v166, v164, v165
	ds_bpermute_b32 v167, v157, v166
	s_waitcnt lgkmcnt(0)
	v_add_f32_e32 v166, v166, v167
	ds_bpermute_b32 v167, v158, v166
	s_waitcnt lgkmcnt(0)
	v_add_f32_e32 v168, v166, v167
	s_and_saveexec_b64 s[56:57], s[4:5]
	global_atomic_add_f32 v149, v168, s[22:23] offset:128
	s_or_b64 exec, exec, s[56:57]
	s_waitcnt vmcnt(23)
	v_add_f32_e32 v228, v76, v228
	v_add_f32_e32 v229, v77, v229
	v_add_f32_e32 v230, v78, v230
	v_add_f32_e32 v231, v79, v231
	v_add_f32_e32 v232, v72, v232
	v_add_f32_e32 v233, v73, v233
	v_add_f32_e32 v234, v74, v234
	v_add_f32_e32 v235, v75, v235
	v_cvt_pk_bf16_f32 v244, v228, v229
	v_cvt_pk_bf16_f32 v245, v230, v231
	v_cvt_pk_bf16_f32 v246, v232, v233
	v_cvt_pk_bf16_f32 v247, v234, v235
	s_add_u32 s62, s12, 0x30000
	s_addc_u32 s63, s13, 0
	v_mul_f32_e32 v160, v229, v229
	v_mul_f32_e32 v161, v231, v231
	v_mul_f32_e32 v162, v233, v233
	v_mul_f32_e32 v163, v235, v235
	v_fmac_f32_e32 v160, v228, v228
	v_fmac_f32_e32 v161, v230, v230
	v_fmac_f32_e32 v162, v232, v232
	v_fmac_f32_e32 v163, v234, v234
	v_add_f32_e32 v160, v160, v161
	v_add_f32_e32 v162, v162, v163
	v_add_f32_e32 v164, v160, v162
	s_add_u32 s60, s36, 0x160000
	s_addc_u32 s61, s37, 0
	global_load_dwordx4 v[228:231], v145, s[60:61] offset:0 nt
	global_load_dwordx4 v[232:235], v145, s[60:61] offset:16 nt
	global_store_dwordx4 v147, v[244:247], s[62:63] offset:0
	s_waitcnt vmcnt(24)
	v_add_f32_e32 v236, v68, v236
	v_add_f32_e32 v237, v69, v237
	v_add_f32_e32 v238, v70, v238
	v_add_f32_e32 v239, v71, v239
	v_add_f32_e32 v240, v64, v240
	v_add_f32_e32 v241, v65, v241
	v_add_f32_e32 v242, v66, v242
	v_add_f32_e32 v243, v67, v243
	v_cvt_pk_bf16_f32 v248, v236, v237
	v_cvt_pk_bf16_f32 v249, v238, v239
	v_cvt_pk_bf16_f32 v250, v240, v241
	v_cvt_pk_bf16_f32 v251, v242, v243
	v_mul_f32_e32 v160, v237, v237
	v_mul_f32_e32 v161, v239, v239
	v_mul_f32_e32 v162, v241, v241
	v_mul_f32_e32 v163, v243, v243
	v_fmac_f32_e32 v160, v236, v236
	v_fmac_f32_e32 v161, v238, v238
	v_fmac_f32_e32 v162, v240, v240
	v_fmac_f32_e32 v163, v242, v242
	v_add_f32_e32 v160, v160, v161
	v_add_f32_e32 v162, v162, v163
	v_add_f32_e32 v165, v160, v162
	global_load_dwordx4 v[236:239], v145, s[60:61] offset:512 nt
	global_load_dwordx4 v[240:243], v145, s[60:61] offset:528 nt
	global_store_dwordx4 v147, v[248:251], s[62:63] offset:256
	v_add_f32_e32 v166, v164, v165
	ds_bpermute_b32 v167, v157, v166
	s_waitcnt lgkmcnt(0)
	v_add_f32_e32 v166, v166, v167
	ds_bpermute_b32 v167, v158, v166
	s_waitcnt lgkmcnt(0)
	v_add_f32_e32 v168, v166, v167
	s_and_saveexec_b64 s[56:57], s[4:5]
	global_atomic_add_f32 v149, v168, s[22:23] offset:192
	s_or_b64 exec, exec, s[56:57]
	s_waitcnt vmcnt(26)
	v_add_f32_e32 v176, v60, v176
	v_add_f32_e32 v177, v61, v177
	v_add_f32_e32 v178, v62, v178
	v_add_f32_e32 v179, v63, v179
	v_add_f32_e32 v180, v56, v180
	v_add_f32_e32 v181, v57, v181
	v_add_f32_e32 v182, v58, v182
	v_add_f32_e32 v183, v59, v183
	v_cvt_pk_bf16_f32 v244, v176, v177
	v_cvt_pk_bf16_f32 v245, v178, v179
	v_cvt_pk_bf16_f32 v246, v180, v181
	v_cvt_pk_bf16_f32 v247, v182, v183
	s_add_u32 s62, s12, 0x80000
	s_addc_u32 s63, s13, 0
	v_mul_f32_e32 v160, v177, v177
	v_mul_f32_e32 v161, v179, v179
	v_mul_f32_e32 v162, v181, v181
	v_mul_f32_e32 v163, v183, v183
	v_fmac_f32_e32 v160, v176, v176
	v_fmac_f32_e32 v161, v178, v178
	v_fmac_f32_e32 v162, v180, v180
	v_fmac_f32_e32 v163, v182, v182
	v_add_f32_e32 v160, v160, v161
	v_add_f32_e32 v162, v162, v163
	v_add_f32_e32 v164, v160, v162
	global_store_dwordx4 v147, v[244:247], s[62:63] offset:0
	s_waitcnt vmcnt(24)
	v_add_f32_e32 v184, v52, v184
	v_add_f32_e32 v185, v53, v185
	v_add_f32_e32 v186, v54, v186
	v_add_f32_e32 v187, v55, v187
	v_add_f32_e32 v188, v48, v188
	v_add_f32_e32 v189, v49, v189
	v_add_f32_e32 v190, v50, v190
	v_add_f32_e32 v191, v51, v191
	v_cvt_pk_bf16_f32 v248, v184, v185
	v_cvt_pk_bf16_f32 v249, v186, v187
	v_cvt_pk_bf16_f32 v250, v188, v189
	v_cvt_pk_bf16_f32 v251, v190, v191
	v_mul_f32_e32 v160, v185, v185
	v_mul_f32_e32 v161, v187, v187
	v_mul_f32_e32 v162, v189, v189
	v_mul_f32_e32 v163, v191, v191
	v_fmac_f32_e32 v160, v184, v184
	v_fmac_f32_e32 v161, v186, v186
	v_fmac_f32_e32 v162, v188, v188
	v_fmac_f32_e32 v163, v190, v190
	v_add_f32_e32 v160, v160, v161
	v_add_f32_e32 v162, v162, v163
	v_add_f32_e32 v165, v160, v162
	global_store_dwordx4 v147, v[248:251], s[62:63] offset:256
	v_add_f32_e32 v166, v164, v165
	ds_bpermute_b32 v167, v157, v166
	s_waitcnt lgkmcnt(0)
	v_add_f32_e32 v166, v166, v167
	ds_bpermute_b32 v167, v158, v166
	s_waitcnt lgkmcnt(0)
	v_add_f32_e32 v168, v166, v167
	s_and_saveexec_b64 s[56:57], s[4:5]
	global_atomic_add_f32 v149, v168, s[22:23] offset:512
	s_or_b64 exec, exec, s[56:57]
	s_waitcnt vmcnt(22)
	v_add_f32_e32 v192, v44, v192
	v_add_f32_e32 v193, v45, v193
	v_add_f32_e32 v194, v46, v194
	v_add_f32_e32 v195, v47, v195
	v_add_f32_e32 v196, v40, v196
	v_add_f32_e32 v197, v41, v197
	v_add_f32_e32 v198, v42, v198
	v_add_f32_e32 v199, v43, v199
	v_cvt_pk_bf16_f32 v244, v192, v193
	v_cvt_pk_bf16_f32 v245, v194, v195
	v_cvt_pk_bf16_f32 v246, v196, v197
	v_cvt_pk_bf16_f32 v247, v198, v199
	s_add_u32 s62, s12, 0x90000
	s_addc_u32 s63, s13, 0
	v_mul_f32_e32 v160, v193, v193
	v_mul_f32_e32 v161, v195, v195
	v_mul_f32_e32 v162, v197, v197
	v_mul_f32_e32 v163, v199, v199
	v_fmac_f32_e32 v160, v192, v192
	v_fmac_f32_e32 v161, v194, v194
	v_fmac_f32_e32 v162, v196, v196
	v_fmac_f32_e32 v163, v198, v198
	v_add_f32_e32 v160, v160, v161
	v_add_f32_e32 v162, v162, v163
	v_add_f32_e32 v164, v160, v162
	global_store_dwordx4 v147, v[244:247], s[62:63] offset:0
	s_waitcnt vmcnt(20)
	v_add_f32_e32 v200, v36, v200
	v_add_f32_e32 v201, v37, v201
	v_add_f32_e32 v202, v38, v202
	v_add_f32_e32 v203, v39, v203
	v_add_f32_e32 v204, v32, v204
	v_add_f32_e32 v205, v33, v205
	v_add_f32_e32 v206, v34, v206
	v_add_f32_e32 v207, v35, v207
	v_cvt_pk_bf16_f32 v248, v200, v201
	v_cvt_pk_bf16_f32 v249, v202, v203
	v_cvt_pk_bf16_f32 v250, v204, v205
	v_cvt_pk_bf16_f32 v251, v206, v207
	v_mul_f32_e32 v160, v201, v201
	v_mul_f32_e32 v161, v203, v203
	v_mul_f32_e32 v162, v205, v205
	v_mul_f32_e32 v163, v207, v207
	v_fmac_f32_e32 v160, v200, v200
	v_fmac_f32_e32 v161, v202, v202
	v_fmac_f32_e32 v162, v204, v204
	v_fmac_f32_e32 v163, v206, v206
	v_add_f32_e32 v160, v160, v161
	v_add_f32_e32 v162, v162, v163
	v_add_f32_e32 v165, v160, v162
	global_store_dwordx4 v147, v[248:251], s[62:63] offset:256
	v_add_f32_e32 v166, v164, v165
	ds_bpermute_b32 v167, v157, v166
	s_waitcnt lgkmcnt(0)
	v_add_f32_e32 v166, v166, v167
	ds_bpermute_b32 v167, v158, v166
	s_waitcnt lgkmcnt(0)
	v_add_f32_e32 v168, v166, v167
	s_and_saveexec_b64 s[56:57], s[4:5]
	global_atomic_add_f32 v149, v168, s[22:23] offset:576
	s_or_b64 exec, exec, s[56:57]
	s_waitcnt vmcnt(18)
	v_add_f32_e32 v208, v28, v208
	v_add_f32_e32 v209, v29, v209
	v_add_f32_e32 v210, v30, v210
	v_add_f32_e32 v211, v31, v211
	v_add_f32_e32 v212, v24, v212
	v_add_f32_e32 v213, v25, v213
	v_add_f32_e32 v214, v26, v214
	v_add_f32_e32 v215, v27, v215
	v_cvt_pk_bf16_f32 v244, v208, v209
	v_cvt_pk_bf16_f32 v245, v210, v211
	v_cvt_pk_bf16_f32 v246, v212, v213
	v_cvt_pk_bf16_f32 v247, v214, v215
	s_add_u32 s62, s12, 0xa0000
	s_addc_u32 s63, s13, 0
	v_mul_f32_e32 v160, v209, v209
	v_mul_f32_e32 v161, v211, v211
	v_mul_f32_e32 v162, v213, v213
	v_mul_f32_e32 v163, v215, v215
	v_fmac_f32_e32 v160, v208, v208
	v_fmac_f32_e32 v161, v210, v210
	v_fmac_f32_e32 v162, v212, v212
	v_fmac_f32_e32 v163, v214, v214
	v_add_f32_e32 v160, v160, v161
	v_add_f32_e32 v162, v162, v163
	v_add_f32_e32 v164, v160, v162
	global_store_dwordx4 v147, v[244:247], s[62:63] offset:0
	s_waitcnt vmcnt(16)
	v_add_f32_e32 v216, v20, v216
	v_add_f32_e32 v217, v21, v217
	v_add_f32_e32 v218, v22, v218
	v_add_f32_e32 v219, v23, v219
	v_add_f32_e32 v220, v16, v220
	v_add_f32_e32 v221, v17, v221
	v_add_f32_e32 v222, v18, v222
	v_add_f32_e32 v223, v19, v223
	v_cvt_pk_bf16_f32 v248, v216, v217
	v_cvt_pk_bf16_f32 v249, v218, v219
	v_cvt_pk_bf16_f32 v250, v220, v221
	v_cvt_pk_bf16_f32 v251, v222, v223
	v_mul_f32_e32 v160, v217, v217
	v_mul_f32_e32 v161, v219, v219
	v_mul_f32_e32 v162, v221, v221
	v_mul_f32_e32 v163, v223, v223
	v_fmac_f32_e32 v160, v216, v216
	v_fmac_f32_e32 v161, v218, v218
	v_fmac_f32_e32 v162, v220, v220
	v_fmac_f32_e32 v163, v222, v222
	v_add_f32_e32 v160, v160, v161
	v_add_f32_e32 v162, v162, v163
	v_add_f32_e32 v165, v160, v162
	global_store_dwordx4 v147, v[248:251], s[62:63] offset:256
	v_add_f32_e32 v166, v164, v165
	ds_bpermute_b32 v167, v157, v166
	s_waitcnt lgkmcnt(0)
	v_add_f32_e32 v166, v166, v167
	ds_bpermute_b32 v167, v158, v166
	s_waitcnt lgkmcnt(0)
	v_add_f32_e32 v168, v166, v167
	s_and_saveexec_b64 s[56:57], s[4:5]
	global_atomic_add_f32 v149, v168, s[22:23] offset:640
	s_or_b64 exec, exec, s[56:57]
	s_waitcnt vmcnt(14)
	v_add_f32_e32 v228, v12, v228
	v_add_f32_e32 v229, v13, v229
	v_add_f32_e32 v230, v14, v230
	v_add_f32_e32 v231, v15, v231
	v_add_f32_e32 v232, v8, v232
	v_add_f32_e32 v233, v9, v233
	v_add_f32_e32 v234, v10, v234
	v_add_f32_e32 v235, v11, v235
	v_cvt_pk_bf16_f32 v244, v228, v229
	v_cvt_pk_bf16_f32 v245, v230, v231
	v_cvt_pk_bf16_f32 v246, v232, v233
	v_cvt_pk_bf16_f32 v247, v234, v235
	s_add_u32 s62, s12, 0xb0000
	s_addc_u32 s63, s13, 0
	v_mul_f32_e32 v160, v229, v229
	v_mul_f32_e32 v161, v231, v231
	v_mul_f32_e32 v162, v233, v233
	v_mul_f32_e32 v163, v235, v235
	v_fmac_f32_e32 v160, v228, v228
	v_fmac_f32_e32 v161, v230, v230
	v_fmac_f32_e32 v162, v232, v232
	v_fmac_f32_e32 v163, v234, v234
	v_add_f32_e32 v160, v160, v161
	v_add_f32_e32 v162, v162, v163
	v_add_f32_e32 v164, v160, v162
	global_store_dwordx4 v147, v[244:247], s[62:63] offset:0
	s_waitcnt vmcnt(12)
	v_add_f32_e32 v236, v4, v236
	v_add_f32_e32 v237, v5, v237
	v_add_f32_e32 v238, v6, v238
	v_add_f32_e32 v239, v7, v239
	v_add_f32_e32 v240, v0, v240
	v_add_f32_e32 v241, v1, v241
	v_add_f32_e32 v242, v2, v242
	v_add_f32_e32 v243, v3, v243
	v_cvt_pk_bf16_f32 v248, v236, v237
	v_cvt_pk_bf16_f32 v249, v238, v239
	v_cvt_pk_bf16_f32 v250, v240, v241
	v_cvt_pk_bf16_f32 v251, v242, v243
	v_mul_f32_e32 v160, v237, v237
	v_mul_f32_e32 v161, v239, v239
	v_mul_f32_e32 v162, v241, v241
	v_mul_f32_e32 v163, v243, v243
	v_fmac_f32_e32 v160, v236, v236
	v_fmac_f32_e32 v161, v238, v238
	v_fmac_f32_e32 v162, v240, v240
	v_fmac_f32_e32 v163, v242, v242
	v_add_f32_e32 v160, v160, v161
	v_add_f32_e32 v162, v162, v163
	v_add_f32_e32 v165, v160, v162
	global_store_dwordx4 v147, v[248:251], s[62:63] offset:256
	v_add_f32_e32 v166, v164, v165
	ds_bpermute_b32 v167, v157, v166
	s_waitcnt lgkmcnt(0)
	v_add_f32_e32 v166, v166, v167
	ds_bpermute_b32 v167, v158, v166
	s_waitcnt lgkmcnt(0)
	v_add_f32_e32 v168, v166, v167
	s_and_saveexec_b64 s[56:57], s[4:5]
	global_atomic_add_f32 v149, v168, s[22:23] offset:704
	s_or_b64 exec, exec, s[56:57]
	s_andn2_b64 vcc, exec, s[6:7]
	s_mov_b64 s[6:7], -1
	s_cbranch_vccnz .LBB0_664
	s_andn2_b64 vcc, exec, s[14:15]
	s_cbranch_vccnz .LBB0_663
	s_barrier
	s_branch .LBB0_663

.LBB0_695:
	s_cmp_eq_u32 s99, 2
	s_cbranch_scc1 .Lp3_after_A2
	s_add_u32 s14, s22, 0xc000000
	v_mov_b32_e32 v8, v225
	s_addc_u32 s15, s23, 0
	s_waitcnt lgkmcnt(0)
	s_barrier
	s_and_b64 vcc, exec, s[8:9]
	v_readfirstlane_b32 s34, v8
	s_cbranch_vccnz .LBB0_717
	s_ashr_i32 s37, s2, 31
	s_lshr_b32 s3, s37, 29
	s_add_i32 s3, s2, s3
	s_and_b32 s4, s3, -8
	s_sub_i32 s7, s2, s4
	s_cmp_gt_i32 s7, -1
	s_cbranch_scc0 .LBB0_698
	s_lshl_b32 s6, s7, 6
	s_cbranch_execz .LBB0_699
	s_branch .LBB0_700

.LBB0_717:
	s_cmp_eq_u32 s99, 1
	s_cbranch_scc0 .Lp3_end
	s_mov_b32 s99, 2
	s_mov_b64 s[36:37], s[100:101]
	s_add_u32 s34, s22, 0x2200000
	s_addc_u32 s35, s23, 0
	v_mov_b32_e32 v8, v225
	s_nop 0
	v_readfirstlane_b32 s6, v8
	s_branch .Lp3_S2
.Lp3_after_A2:
	s_add_u32 s14, s22, 0xc000000
	s_addc_u32 s15, s23, 0

	.amdhsa_kernel _Z14fwd_megakernel4Args
		.amdhsa_group_segment_fixed_size 0
		.amdhsa_private_segment_fixed_size 0
		.amdhsa_kernarg_size 384
		.amdhsa_user_sgpr_count 2
		.amdhsa_user_sgpr_dispatch_ptr 0
		.amdhsa_user_sgpr_queue_ptr 0
		.amdhsa_user_sgpr_kernarg_segment_ptr 1
		.amdhsa_user_sgpr_dispatch_id 0
		.amdhsa_user_sgpr_kernarg_preload_length 0
		.amdhsa_user_sgpr_kernarg_preload_offset 0
		.amdhsa_user_sgpr_private_segment_size 0
		.amdhsa_uses_dynamic_stack 0
		.amdhsa_enable_private_segment 0
		.amdhsa_system_sgpr_workgroup_id_x 1
		.amdhsa_system_sgpr_workgroup_id_y 0
		.amdhsa_system_sgpr_workgroup_id_z 0
		.amdhsa_system_sgpr_workgroup_info 0
		.amdhsa_system_vgpr_workitem_id 2
		.amdhsa_next_free_vgpr 256
		.amdhsa_next_free_sgpr 102
		.amdhsa_accum_offset 256
		.amdhsa_reserve_vcc 1
		.amdhsa_float_round_mode_32 0
		.amdhsa_float_round_mode_16_64 0
		.amdhsa_float_denorm_mode_32 3
		.amdhsa_float_denorm_mode_16_64 3
		.amdhsa_dx10_clamp 1
		.amdhsa_ieee_mode 1
		.amdhsa_fp16_overflow 0
		.amdhsa_tg_split 0
		.amdhsa_exception_fp_ieee_invalid_op 0
		.amdhsa_exception_fp_denorm_src 0
		.amdhsa_exception_fp_ieee_div_zero 0
		.amdhsa_exception_fp_ieee_overflow 0
		.amdhsa_exception_fp_ieee_underflow 0
		.amdhsa_exception_fp_ieee_inexact 0
		.amdhsa_exception_int_div_zero 0
	.end_amdhsa_kernel

amdhsa.kernels:
  - .agpr_count:     0
    .args:
      - .offset:         0
        .size:           128
        .value_kind:     by_value
      - .offset:         128
        .size:           4
        .value_kind:     hidden_block_count_x
      - .offset:         132
        .size:           4
        .value_kind:     hidden_block_count_y
      - .offset:         136
        .size:           4
        .value_kind:     hidden_block_count_z
      - .offset:         140
        .size:           2
        .value_kind:     hidden_group_size_x
      - .offset:         142
        .size:           2
        .value_kind:     hidden_group_size_y
      - .offset:         144
        .size:           2
        .value_kind:     hidden_group_size_z
      - .offset:         146
        .size:           2
        .value_kind:     hidden_remainder_x
      - .offset:         148
        .size:           2
        .value_kind:     hidden_remainder_y
      - .offset:         150
        .size:           2
        .value_kind:     hidden_remainder_z
      - .offset:         168
        .size:           8
        .value_kind:     hidden_global_offset_x
      - .offset:         176
        .size:           8
        .value_kind:     hidden_global_offset_y
      - .offset:         184
        .size:           8
        .value_kind:     hidden_global_offset_z
      - .offset:         192
        .size:           2
        .value_kind:     hidden_grid_dims
      - .offset:         216
        .size:           8
        .value_kind:     hidden_multigrid_sync_arg
      - .offset:         248
        .size:           4
        .value_kind:     hidden_dynamic_lds_size
    .group_segment_fixed_size: 0
    .kernarg_segment_align: 8
    .kernarg_segment_size: 384
    .language:       OpenCL C
    .language_version:
      - 2
      - 0
    .max_flat_workgroup_size: 512
    .name:           _Z14fwd_megakernel4Args
    .private_segment_fixed_size: 0
    .sgpr_count:     108
    .sgpr_spill_count: 0
    .symbol:         _Z14fwd_megakernel4Args.kd
    .uniform_work_group_size: 1
    .uses_dynamic_stack: false
    .vgpr_count:     256
    .vgpr_spill_count: 0
    .wavefront_size: 64
